# attention: P.V fragment LDS addresses folded into DS immediates (8 VALU adds fewer per key chunk)
# speedup vs baseline: 1.0017x; 1.0017x over previous
.LBB0_1070:
	s_nop 1
	ds_bpermute_b32 v80, v126, v137
	v_max_f32_e32 v81, v137, v137
	s_waitcnt lgkmcnt(0)
	v_max_f32_e32 v80, v80, v80
	v_max_f32_e32 v80, v81, v80
	ds_bpermute_b32 v81, v125, v80
	s_waitcnt lgkmcnt(0)
	v_max3_f32 v88, v136, v80, v81
	v_sub_f32_e32 v80, v136, v88
	v_exp_f32_e32 v90, v80
	v_sub_f32_e32 v80, v120, v88
	v_exp_f32_e32 v80, v80
	v_sub_f32_e32 v82, v121, v88
	v_exp_f32_e32 v82, v82
	v_sub_f32_e32 v83, v112, v88
	v_exp_f32_e32 v83, v83
	v_sub_f32_e32 v84, v113, v88
	v_exp_f32_e32 v84, v84
	v_sub_f32_e32 v85, v108, v88
	v_fma_f32 v81, v135, v90, v80
	v_exp_f32_e32 v85, v85
	v_sub_f32_e32 v86, v109, v88
	v_add_f32_e32 v81, v82, v81
	v_exp_f32_e32 v86, v86
	v_sub_f32_e32 v87, v106, v88
	v_add_f32_e32 v81, v83, v81
	v_exp_f32_e32 v87, v87
	v_sub_f32_e32 v89, v107, v88
	v_add_f32_e32 v81, v84, v81
	v_exp_f32_e32 v89, v89
	v_add_f32_e32 v81, v85, v81
	v_add_f32_e32 v81, v86, v81
	v_add_f32_e32 v81, v87, v81
	v_add_f32_e32 v91, v89, v81
	v_cvt_pk_bf16_f32 v81, v83, v84
	v_sub_f32_e32 v84, v110, v88
	v_cvt_pk_bf16_f32 v83, v87, v89
	v_exp_f32_e32 v89, v84
	v_sub_f32_e32 v84, v111, v88
	v_exp_f32_e32 v92, v84
	v_sub_f32_e32 v84, v114, v88
	v_exp_f32_e32 v93, v84
	v_sub_f32_e32 v84, v115, v88
	v_exp_f32_e32 v94, v84
	v_sub_f32_e32 v84, v116, v88
	v_exp_f32_e32 v95, v84
	v_sub_f32_e32 v84, v117, v88
	v_exp_f32_e32 v106, v84
	v_sub_f32_e32 v84, v118, v88
	v_exp_f32_e32 v107, v84
	v_sub_f32_e32 v84, v119, v88
	v_exp_f32_e32 v135, v84
	v_cvt_pk_bf16_f32 v84, v89, v92
	v_add_f32_e32 v89, v89, v91
	v_add_f32_e32 v89, v92, v89
	v_add_f32_e32 v89, v93, v89
	v_add_f32_e32 v89, v94, v89
	v_add_f32_e32 v89, v95, v89
	v_cvt_pk_bf16_f32 v80, v80, v82
	v_cvt_pk_bf16_f32 v82, v85, v86
	v_cvt_pk_bf16_f32 v85, v93, v94
	v_add_f32_e32 v89, v106, v89
	v_cvt_pk_bf16_f32 v86, v95, v106
	v_cvt_pk_bf16_f32 v87, v107, v135
	v_pk_mul_f32 v[74:75], v[74:75], v[90:91] op_sel_hi:[1,0]
	v_pk_mul_f32 v[72:73], v[72:73], v[90:91] op_sel_hi:[1,0]
	v_pk_mul_f32 v[70:71], v[70:71], v[90:91] op_sel_hi:[1,0]
	v_pk_mul_f32 v[68:69], v[68:69], v[90:91] op_sel_hi:[1,0]
	v_pk_mul_f32 v[58:59], v[58:59], v[90:91] op_sel_hi:[1,0]
	v_pk_mul_f32 v[56:57], v[56:57], v[90:91] op_sel_hi:[1,0]
	v_pk_mul_f32 v[18:19], v[18:19], v[90:91] op_sel_hi:[1,0]
	v_pk_mul_f32 v[16:17], v[16:17], v[90:91] op_sel_hi:[1,0]
	v_pk_mul_f32 v[30:31], v[30:31], v[90:91] op_sel_hi:[1,0]
	v_pk_mul_f32 v[28:29], v[28:29], v[90:91] op_sel_hi:[1,0]
	v_pk_mul_f32 v[22:23], v[22:23], v[90:91] op_sel_hi:[1,0]
	v_pk_mul_f32 v[20:21], v[20:21], v[90:91] op_sel_hi:[1,0]
	v_pk_mul_f32 v[26:27], v[26:27], v[90:91] op_sel_hi:[1,0]
	v_pk_mul_f32 v[24:25], v[24:25], v[90:91] op_sel_hi:[1,0]
	v_pk_mul_f32 v[78:79], v[78:79], v[90:91] op_sel_hi:[1,0]
	v_pk_mul_f32 v[76:77], v[76:77], v[90:91] op_sel_hi:[1,0]
	v_add_f32_e32 v89, v107, v89
	ds_read_b128 v[90:93], v134 offset:34816
	ds_read_b128 v[106:109], v134 offset:34880
	ds_read_b128 v[110:113], v134 offset:37120
	ds_read_b128 v[114:117], v134 offset:37184
	ds_read_b128 v[118:121], v134 offset:39424
	ds_read_b128 v[136:139], v134 offset:39488
	ds_read_b128 v[140:143], v134 offset:41728
	ds_read_b128 v[144:147], v134 offset:41792
	s_waitcnt lgkmcnt(7)
	v_mfma_f32_16x16x32_bf16 v[72:75], v[90:93], v[80:83], v[72:75]
	s_waitcnt lgkmcnt(5)
	v_mfma_f32_16x16x32_bf16 v[68:71], v[110:113], v[80:83], v[68:71]
	s_waitcnt lgkmcnt(3)
	v_mfma_f32_16x16x32_bf16 v[56:59], v[118:121], v[80:83], v[56:59]
	s_waitcnt lgkmcnt(1)
	v_mfma_f32_16x16x32_bf16 v[16:19], v[140:143], v[80:83], v[16:19]
	v_mfma_f32_16x16x32_bf16 v[72:75], v[106:109], v[84:87], v[72:75]
	v_mfma_f32_16x16x32_bf16 v[68:71], v[114:117], v[84:87], v[68:71]
	v_mfma_f32_16x16x32_bf16 v[56:59], v[136:139], v[84:87], v[56:59]
	s_waitcnt lgkmcnt(0)
	v_mfma_f32_16x16x32_bf16 v[16:19], v[144:147], v[84:87], v[16:19]
	ds_read_b128 v[90:93], v134 offset:44032
	ds_read_b128 v[106:109], v134 offset:44096
	ds_read_b128 v[110:113], v134 offset:46336
	ds_read_b128 v[114:117], v134 offset:46400
	ds_read_b128 v[118:121], v134 offset:48640
	ds_read_b128 v[136:139], v134 offset:48704
	ds_read_b128 v[140:143], v134 offset:50944
	ds_read_b128 v[144:147], v134 offset:51008
	s_waitcnt lgkmcnt(7)
	v_mfma_f32_16x16x32_bf16 v[28:31], v[90:93], v[80:83], v[28:31]
	s_waitcnt lgkmcnt(5)
	v_mfma_f32_16x16x32_bf16 v[20:23], v[110:113], v[80:83], v[20:23]
	s_waitcnt lgkmcnt(3)
	v_mfma_f32_16x16x32_bf16 v[24:27], v[118:121], v[80:83], v[24:27]
	s_waitcnt lgkmcnt(1)
	v_mfma_f32_16x16x32_bf16 v[76:79], v[140:143], v[80:83], v[76:79]
	v_mfma_f32_16x16x32_bf16 v[28:31], v[106:109], v[84:87], v[28:31]
	v_mfma_f32_16x16x32_bf16 v[20:23], v[114:117], v[84:87], v[20:23]
	v_mfma_f32_16x16x32_bf16 v[24:27], v[136:139], v[84:87], v[24:27]
	s_waitcnt lgkmcnt(0)
	v_mfma_f32_16x16x32_bf16 v[76:79], v[144:147], v[84:87], v[76:79]
	v_add_f32_e32 v135, v135, v89
	s_andn2_b64 vcc, exec, s[76:77]
	s_add_i32 s39, s39, 1
	s_cbranch_vccz .LBB0_1072
	v_mov_b32_e32 v136, v88
	v_add_u32_e32 v131, s32, v131
	v_add_u32_e32 v132, s32, v132
	v_add_u32_e32 v148, s32, v148
	v_add_u32_e32 v133, s32, v133
	v_add_u32_e32 v134, s32, v134
	s_sub_i32 s32, 0, s32
	s_branch .LBB0_1056

.LBB0_1124:
	s_nop 1
	ds_bpermute_b32 v80, v126, v137
	v_max_f32_e32 v81, v137, v137
	s_waitcnt lgkmcnt(0)
	v_max_f32_e32 v80, v80, v80
	v_max_f32_e32 v80, v81, v80
	ds_bpermute_b32 v81, v125, v80
	s_waitcnt lgkmcnt(0)
	v_max3_f32 v88, v136, v80, v81
	v_sub_f32_e32 v80, v136, v88
	v_exp_f32_e32 v90, v80
	v_sub_f32_e32 v80, v120, v88
	v_exp_f32_e32 v80, v80
	v_sub_f32_e32 v82, v121, v88
	v_exp_f32_e32 v82, v82
	v_sub_f32_e32 v83, v112, v88
	v_exp_f32_e32 v83, v83
	v_sub_f32_e32 v84, v113, v88
	v_exp_f32_e32 v84, v84
	v_sub_f32_e32 v85, v108, v88
	v_fma_f32 v81, v135, v90, v80
	v_exp_f32_e32 v85, v85
	v_sub_f32_e32 v86, v109, v88
	v_add_f32_e32 v81, v82, v81
	v_exp_f32_e32 v86, v86
	v_sub_f32_e32 v87, v106, v88
	v_add_f32_e32 v81, v83, v81
	v_exp_f32_e32 v87, v87
	v_sub_f32_e32 v89, v107, v88
	v_add_f32_e32 v81, v84, v81
	v_exp_f32_e32 v89, v89
	v_add_f32_e32 v81, v85, v81
	v_add_f32_e32 v81, v86, v81
	v_add_f32_e32 v81, v87, v81
	v_add_f32_e32 v91, v89, v81
	v_cvt_pk_bf16_f32 v81, v83, v84
	v_sub_f32_e32 v84, v110, v88
	v_cvt_pk_bf16_f32 v83, v87, v89
	v_exp_f32_e32 v89, v84
	v_sub_f32_e32 v84, v111, v88
	v_exp_f32_e32 v92, v84
	v_sub_f32_e32 v84, v114, v88
	v_exp_f32_e32 v93, v84
	v_sub_f32_e32 v84, v115, v88
	v_exp_f32_e32 v94, v84
	v_sub_f32_e32 v84, v116, v88
	v_exp_f32_e32 v95, v84
	v_sub_f32_e32 v84, v117, v88
	v_exp_f32_e32 v106, v84
	v_sub_f32_e32 v84, v118, v88
	v_exp_f32_e32 v107, v84
	v_sub_f32_e32 v84, v119, v88
	v_exp_f32_e32 v135, v84
	v_cvt_pk_bf16_f32 v84, v89, v92
	v_add_f32_e32 v89, v89, v91
	v_add_f32_e32 v89, v92, v89
	v_add_f32_e32 v89, v93, v89
	v_add_f32_e32 v89, v94, v89
	v_add_f32_e32 v89, v95, v89
	v_cvt_pk_bf16_f32 v80, v80, v82
	v_cvt_pk_bf16_f32 v82, v85, v86
	v_cvt_pk_bf16_f32 v85, v93, v94
	v_add_f32_e32 v89, v106, v89
	v_cvt_pk_bf16_f32 v86, v95, v106
	v_cvt_pk_bf16_f32 v87, v107, v135
	v_pk_mul_f32 v[74:75], v[74:75], v[90:91] op_sel_hi:[1,0]
	v_pk_mul_f32 v[72:73], v[72:73], v[90:91] op_sel_hi:[1,0]
	v_pk_mul_f32 v[70:71], v[70:71], v[90:91] op_sel_hi:[1,0]
	v_pk_mul_f32 v[68:69], v[68:69], v[90:91] op_sel_hi:[1,0]
	v_pk_mul_f32 v[58:59], v[58:59], v[90:91] op_sel_hi:[1,0]
	v_pk_mul_f32 v[56:57], v[56:57], v[90:91] op_sel_hi:[1,0]
	v_pk_mul_f32 v[18:19], v[18:19], v[90:91] op_sel_hi:[1,0]
	v_pk_mul_f32 v[16:17], v[16:17], v[90:91] op_sel_hi:[1,0]
	v_pk_mul_f32 v[30:31], v[30:31], v[90:91] op_sel_hi:[1,0]
	v_pk_mul_f32 v[28:29], v[28:29], v[90:91] op_sel_hi:[1,0]
	v_pk_mul_f32 v[22:23], v[22:23], v[90:91] op_sel_hi:[1,0]
	v_pk_mul_f32 v[20:21], v[20:21], v[90:91] op_sel_hi:[1,0]
	v_pk_mul_f32 v[26:27], v[26:27], v[90:91] op_sel_hi:[1,0]
	v_pk_mul_f32 v[24:25], v[24:25], v[90:91] op_sel_hi:[1,0]
	v_pk_mul_f32 v[78:79], v[78:79], v[90:91] op_sel_hi:[1,0]
	v_pk_mul_f32 v[76:77], v[76:77], v[90:91] op_sel_hi:[1,0]
	v_add_f32_e32 v89, v107, v89
	ds_read_b128 v[90:93], v134 offset:34816
	ds_read_b128 v[106:109], v134 offset:34880
	ds_read_b128 v[110:113], v134 offset:37120
	ds_read_b128 v[114:117], v134 offset:37184
	ds_read_b128 v[118:121], v134 offset:39424
	ds_read_b128 v[136:139], v134 offset:39488
	ds_read_b128 v[140:143], v134 offset:41728
	ds_read_b128 v[144:147], v134 offset:41792
	s_waitcnt lgkmcnt(7)
	v_mfma_f32_16x16x32_bf16 v[72:75], v[90:93], v[80:83], v[72:75]
	s_waitcnt lgkmcnt(5)
	v_mfma_f32_16x16x32_bf16 v[68:71], v[110:113], v[80:83], v[68:71]
	s_waitcnt lgkmcnt(3)
	v_mfma_f32_16x16x32_bf16 v[56:59], v[118:121], v[80:83], v[56:59]
	s_waitcnt lgkmcnt(1)
	v_mfma_f32_16x16x32_bf16 v[16:19], v[140:143], v[80:83], v[16:19]
	v_mfma_f32_16x16x32_bf16 v[72:75], v[106:109], v[84:87], v[72:75]
	v_mfma_f32_16x16x32_bf16 v[68:71], v[114:117], v[84:87], v[68:71]
	v_mfma_f32_16x16x32_bf16 v[56:59], v[136:139], v[84:87], v[56:59]
	s_waitcnt lgkmcnt(0)
	v_mfma_f32_16x16x32_bf16 v[16:19], v[144:147], v[84:87], v[16:19]
	ds_read_b128 v[90:93], v134 offset:44032
	ds_read_b128 v[106:109], v134 offset:44096
	ds_read_b128 v[110:113], v134 offset:46336
	ds_read_b128 v[114:117], v134 offset:46400
	ds_read_b128 v[118:121], v134 offset:48640
	ds_read_b128 v[136:139], v134 offset:48704
	ds_read_b128 v[140:143], v134 offset:50944
	ds_read_b128 v[144:147], v134 offset:51008
	s_waitcnt lgkmcnt(7)
	v_mfma_f32_16x16x32_bf16 v[28:31], v[90:93], v[80:83], v[28:31]
	s_waitcnt lgkmcnt(5)
	v_mfma_f32_16x16x32_bf16 v[20:23], v[110:113], v[80:83], v[20:23]
	s_waitcnt lgkmcnt(3)
	v_mfma_f32_16x16x32_bf16 v[24:27], v[118:121], v[80:83], v[24:27]
	s_waitcnt lgkmcnt(1)
	v_mfma_f32_16x16x32_bf16 v[76:79], v[140:143], v[80:83], v[76:79]
	v_mfma_f32_16x16x32_bf16 v[28:31], v[106:109], v[84:87], v[28:31]
	v_mfma_f32_16x16x32_bf16 v[20:23], v[114:117], v[84:87], v[20:23]
	v_mfma_f32_16x16x32_bf16 v[24:27], v[136:139], v[84:87], v[24:27]
	s_waitcnt lgkmcnt(0)
	v_mfma_f32_16x16x32_bf16 v[76:79], v[144:147], v[84:87], v[76:79]
	v_add_f32_e32 v135, v135, v89
	s_andn2_b64 vcc, exec, s[76:77]
	s_add_i32 s42, s42, 1
	s_cbranch_vccz .LBB0_1100
	v_mov_b32_e32 v136, v88
	v_add_u32_e32 v131, s32, v131
	v_add_u32_e32 v132, s32, v132
	v_add_u32_e32 v148, s32, v148
	v_add_u32_e32 v133, s32, v133
	v_add_u32_e32 v134, s32, v134
	s_sub_i32 s32, 0, s32
	s_branch .LBB0_1110
